# GEMM_out main loop too: substep-1 fragment reads into second register set (v232-v255) in the MFMA shadows of substep 0 (on top of the GEMM_in version)
# speedup vs baseline: 1.0126x; 1.0073x over previous
; DI f32x16 mfma32(bf16x8 a, bf16x8 b, f32x16 c) { return __builtin_amdgcn_mfma_f32_32x32x16_bf16(a, b, c, 0, 0, 0); }
; #define RAW_BARRIER() do { asm volatile("s_waitcnt lgkmcnt(0)" ::: "memory"); __builtin_amdgcn_s_barrier(); } while (0)
; DI void gemm_tile(const Params& p, const GemmJob& j, int mt, int nt, char* smem) {
;     ...
;   for (int kt = 0; kt < nk; ++kt) {
;     if (kt + 1 < nk) asm volatile("s_waitcnt vmcnt(6)" ::: "memory"); else asm volatile("s_waitcnt vmcnt(0)" ::: "memory");
;     RAW_BARRIER();
;     if (kt + 2 < nk) glds(kt + 2, st2);
;     const char* sb = smem + st * GSTAGE;
; #pragma unroll
;     for (int ks = 0; ks < 2; ++ks) {
;       const int off = ks ? (o0 ^ 32) : o0;
;       bf16x8 wf[2], xf[4];
; #pragma unroll
;       for (int a = 0; a < 2; ++a) wf[a] = *(const bf16x8*)(sb + (64 * wn + 32 * a + r) * 64 + off);
; #pragma unroll
;       for (int b = 0; b < 4; ++b) xf[b] = *(const bf16x8*)(sb + 8192 + (128 * wt + 32 * b + r) * 64 + off);
; #pragma unroll
;       for (int a = 0; a < 2; ++a)
; #pragma unroll
;         for (int b = 0; b < 4; ++b) acc[a][b] = mfma32(wf[a], xf[b], acc[a][b]);
;     }
;     st = (st == 2) ? 0 : st + 1; st2 = (st2 == 2) ? 0 : st2 + 1;
.LBB0_886:
	s_mul_i32 s10, s54, 0x6000
	s_add_i32 s36, s10, 0
	v_lshl_add_u64 v[142:143], v[132:133], 0, v[0:1]
	s_mov_b64 s[10:11], 0x20000
	s_add_i32 s37, s36, s55
	s_waitcnt vmcnt(6)
	v_lshl_add_u64 v[144:145], v[142:143], 0, s[10:11]
	s_mov_b32 m0, s37
	s_mov_b64 s[10:11], 0x21000
	s_add_i32 s38, s36, s58
	s_waitcnt lgkmcnt(0)
	s_barrier
	global_load_lds_dwordx4 v[144:145], off
	v_lshl_add_u64 v[142:143], v[142:143], 0, s[10:11]
	s_mov_b32 m0, s38
	s_mov_b64 s[10:11], 0x401000
	global_load_lds_dwordx4 v[142:143], off
	v_lshl_add_u64 v[142:143], v[130:131], 0, v[0:1]
	v_lshl_add_u64 v[144:145], v[142:143], 0, s[92:93]
	s_add_i32 m0, s37, 0x2000
	v_lshl_add_u64 v[130:131], v[130:131], 0, s[88:89]
	global_load_lds_dwordx4 v[144:145], off
	v_lshl_add_u64 v[144:145], v[142:143], 0, s[10:11]
	s_add_i32 m0, s38, 0x2000
	s_add_i32 s10, s36, s62
	global_load_lds_dwordx4 v[144:145], off
	v_lshl_add_u64 v[144:145], v[142:143], 0, s[84:85]
	s_add_i32 m0, s10, 0x2000
	s_add_i32 s10, s36, s63
	global_load_lds_dwordx4 v[144:145], off
	v_lshl_add_u64 v[142:143], v[142:143], 0, s[52:53]
	s_add_i32 m0, s10, 0x2000
	s_mul_i32 s10, s6, 0x6000
	global_load_lds_dwordx4 v[142:143], off
	s_add_i32 s10, s10, 0
	v_add_u32_e32 v141, s10, v137
	v_add_u32_e32 v146, v141, v140
	v_add_u32_e32 v141, v141, v139
	v_add_u32_e32 v252, s10, v138
	v_add_u32_e32 v236, v252, v140
	v_add_u32_e32 v252, v252, v139
	ds_read_b128 v[142:145], v146
	ds_read_b128 v[146:149], v146 offset:2048
	ds_read_b128 v[150:153], v141 offset:8192
	ds_read_b128 v[154:157], v141 offset:10240
	ds_read_b128 v[158:161], v141 offset:12288
	ds_read_b128 v[162:165], v141 offset:14336
	s_waitcnt lgkmcnt(0)
	v_mfma_f32_32x32x16_bf16 v[82:97], v[142:145], v[150:153], v[82:97]
	ds_read_b128 v[232:235], v236
	s_add_i32 s10, s6, 1
	s_cmp_lg_u32 s6, 2
	s_cselect_b32 s6, s10, 0
	s_add_i32 s10, s54, 1
	s_cmp_lg_u32 s54, 2
	s_cselect_b32 s54, s10, 0
	v_mfma_f32_32x32x16_bf16 v[50:65], v[142:145], v[154:157], v[50:65]
	ds_read_b128 v[236:239], v236 offset:2048
	s_add_i32 s7, s7, -1
	v_lshl_add_u64 v[132:133], v[132:133], 0, s[56:57]
	s_cmp_eq_u32 s7, 0
	v_mfma_f32_32x32x16_bf16 v[18:33], v[142:145], v[158:161], v[18:33]
	ds_read_b128 v[240:243], v252 offset:8192
	v_mfma_f32_32x32x16_bf16 v[2:17], v[142:145], v[162:165], v[2:17]
	ds_read_b128 v[244:247], v252 offset:10240
	v_mfma_f32_32x32x16_bf16 v[114:129], v[146:149], v[150:153], v[114:129]
	ds_read_b128 v[248:251], v252 offset:12288
	v_mfma_f32_32x32x16_bf16 v[98:113], v[146:149], v[154:157], v[98:113]
	ds_read_b128 v[252:255], v252 offset:14336
	v_mfma_f32_32x32x16_bf16 v[66:81], v[146:149], v[158:161], v[66:81]
	v_mfma_f32_32x32x16_bf16 v[34:49], v[146:149], v[162:165], v[34:49]
	s_waitcnt lgkmcnt(0)
	v_mfma_f32_32x32x16_bf16 v[82:97], v[232:235], v[240:243], v[82:97]
	v_mfma_f32_32x32x16_bf16 v[50:65], v[232:235], v[244:247], v[50:65]
	v_mfma_f32_32x32x16_bf16 v[18:33], v[232:235], v[248:251], v[18:33]
	v_mfma_f32_32x32x16_bf16 v[2:17], v[232:235], v[252:255], v[2:17]
	v_mfma_f32_32x32x16_bf16 v[114:129], v[236:239], v[240:243], v[114:129]
	v_mfma_f32_32x32x16_bf16 v[98:113], v[236:239], v[244:247], v[98:113]
	v_mfma_f32_32x32x16_bf16 v[66:81], v[236:239], v[248:251], v[66:81]
	v_mfma_f32_32x32x16_bf16 v[34:49], v[236:239], v[252:255], v[34:49]
	s_cbranch_scc0 .LBB0_886
	s_mul_i32 s7, s6, 0x6000
	s_add_i32 s10, s7, 0
	v_add_u32_e32 v0, s10, v137
	s_waitcnt vmcnt(6)
	v_add_u32_e32 v141, v0, v140
	s_waitcnt lgkmcnt(0)
	s_barrier
	ds_read_b128 v[130:133], v141
	ds_read_b128 v[142:145], v141 offset:2048
	v_add_u32_e32 v0, v0, v139
	ds_read_b128 v[146:149], v0 offset:8192
	ds_read_b128 v[150:153], v0 offset:10240
	ds_read_b128 v[154:157], v0 offset:12288
	ds_read_b128 v[158:161], v0 offset:14336
	s_waitcnt lgkmcnt(0)
	v_mfma_f32_32x32x16_bf16 v[82:97], v[130:133], v[146:149], v[82:97]
	v_add_u32_e32 v0, s10, v138
	v_add_u32_e32 v141, v0, v140
	v_add_u32_e32 v0, v0, v139
	s_addk_i32 s7, 0x6000
	s_cmp_lg_u32 s6, 2
	s_cselect_b32 s6, s7, 0
	s_add_i32 s6, s6, 0
	v_mfma_f32_32x32x16_bf16 v[114:129], v[142:145], v[146:149], v[114:129]
	v_readlane_b32 s12, v229, 29
	v_readlane_b32 s22, v229, 39
	v_readlane_b32 s23, v229, 40
	v_readlane_b32 s18, v229, 35
	v_readlane_b32 s19, v229, 36
	s_mov_b32 s58, 0
	v_readlane_b32 s13, v229, 30
	v_mfma_f32_32x32x16_bf16 v[50:65], v[130:133], v[150:153], v[50:65]
	v_readlane_b32 s14, v229, 31
	v_readlane_b32 s15, v229, 32
	v_readlane_b32 s16, v229, 33
	v_readlane_b32 s17, v229, 34
	v_readlane_b32 s20, v229, 37
	v_readlane_b32 s21, v229, 38
	v_readlane_b32 s24, v229, 41
	v_mfma_f32_32x32x16_bf16 v[18:33], v[130:133], v[154:157], v[18:33]
	v_readlane_b32 s25, v229, 42
	v_readlane_b32 s26, v229, 43
	v_readlane_b32 s27, v229, 44
	v_mfma_f32_32x32x16_bf16 v[2:17], v[130:133], v[158:161], v[2:17]
	v_mfma_f32_32x32x16_bf16 v[98:113], v[142:145], v[150:153], v[98:113]
	v_mfma_f32_32x32x16_bf16 v[66:81], v[142:145], v[154:157], v[66:81]
	v_mfma_f32_32x32x16_bf16 v[34:49], v[142:145], v[158:161], v[34:49]
	ds_read_b128 v[130:133], v141
	ds_read_b128 v[142:145], v141 offset:2048
	ds_read_b128 v[146:149], v0 offset:8192
	ds_read_b128 v[150:153], v0 offset:10240
	ds_read_b128 v[154:157], v0 offset:12288
	ds_read_b128 v[158:161], v0 offset:14336
	v_add_u32_e32 v0, s6, v137
	s_waitcnt vmcnt(0)
	v_add_u32_e32 v137, v0, v140
	s_waitcnt lgkmcnt(0)
	s_barrier
; DI unsigned pack2(float a, float b) { f32x2 v = {a, b}; bf16x2_t r = __builtin_convertvector(v, bf16x2_t); return __builtin_bit_cast(unsigned, r); }
; DI void gemm_tile(const Params& p, const GemmJob& j, int mt, int nt, char* smem) {
;     ...
;   for (int kt = 0; kt < nk; ++kt) {
;     if (kt + 1 < nk) asm volatile("s_waitcnt vmcnt(6)" ::: "memory"); else asm volatile("s_waitcnt vmcnt(0)" ::: "memory");
;     RAW_BARRIER();
;     if (kt + 2 < nk) glds(kt + 2, st2);
;     const char* sb = smem + st * GSTAGE;
; #pragma unroll
;     for (int ks = 0; ks < 2; ++ks) {
;       const int off = ks ? (o0 ^ 32) : o0;
;       bf16x8 wf[2], xf[4];
; #pragma unroll
;       for (int a = 0; a < 2; ++a) wf[a] = *(const bf16x8*)(sb + (64 * wn + 32 * a + r) * 64 + off);
; #pragma unroll
;       for (int b = 0; b < 4; ++b) xf[b] = *(const bf16x8*)(sb + 8192 + (128 * wt + 32 * b + r) * 64 + off);
; #pragma unroll
;       for (int a = 0; a < 2; ++a)
; #pragma unroll
;         for (int b = 0; b < 4; ++b) acc[a][b] = mfma32(wf[a], xf[b], acc[a][b]);
;     }
;     st = (st == 2) ? 0 : st + 1; st2 = (st2 == 2) ? 0 : st2 + 1;
;   }
;     ...
;     bf16_t* Cs = (bf16_t*)smem;
; #pragma unroll
;     for (int ni = 0; ni < 4; ++ni)
; #pragma unroll
;       for (int mi = 0; mi < 2; ++mi)
; #pragma unroll
;         for (int g = 0; g < 4; ++g)
;           *(u32x2*)(Cs + (128 * wt + 32 * ni + r) * 136 + 64 * wn + 32 * mi + 8 * g + 4 * h) =
;               (u32x2){pack2(acc[mi][ni][4 * g], acc[mi][ni][4 * g + 1]), pack2(acc[mi][ni][4 * g + 2], acc[mi][ni][4 * g + 3])};
;     __syncthreads();
; #pragma unroll 4
;     for (int q = 0; q < 16; ++q) {
;       const int idx = tid + 256 * q, row = idx >> 4, col = (idx & 15) * 8;
;       const u32x4 av = *(const u32x4*)(Cs + row * 136 + col);
;       bf16_t* xq = j.xbp + blk(t0 + row, n0 + col, NTOK);
;       float rv[8];
;       if (j.res) {
;         const f32x4 r0 = *(const f32x4*)(j.res + (size_t)(t0 + row) * 1024 + n0 + col), r1 = *(const f32x4*)(j.res + (size_t)(t0 + row) * 1024 + n0 + col + 4);
;         rv[0] = r0[0]; rv[1] = r0[1]; rv[2] = r0[2]; rv[3] = r0[3]; rv[4] = r1[0]; rv[5] = r1[1]; rv[6] = r1[2]; rv[7] = r1[3];
;       } else {
;         const u32x4 rb = *(const u32x4*)xq;
; #pragma unroll
;         for (int e = 0; e < 4; ++e) { rv[2 * e] = bflo(rb[e]); rv[2 * e + 1] = bfhi(rb[e]); }
;       }
;       float o[8]; float ss = 0.f;
; #pragma unroll
	s_waitcnt lgkmcnt(0)
	v_mfma_f32_32x32x16_bf16 v[82:97], v[130:133], v[146:149], v[82:97]
	v_add_u32_e32 v0, v0, v139
	v_mfma_f32_32x32x16_bf16 v[114:129], v[142:145], v[146:149], v[114:129]
	v_mfma_f32_32x32x16_bf16 v[50:65], v[130:133], v[150:153], v[50:65]
	v_mfma_f32_32x32x16_bf16 v[18:33], v[130:133], v[154:157], v[18:33]
	v_mfma_f32_32x32x16_bf16 v[2:17], v[130:133], v[158:161], v[2:17]
	v_mfma_f32_32x32x16_bf16 v[98:113], v[142:145], v[150:153], v[98:113]
	v_mfma_f32_32x32x16_bf16 v[66:81], v[142:145], v[154:157], v[66:81]
	v_mfma_f32_32x32x16_bf16 v[34:49], v[142:145], v[158:161], v[34:49]
	ds_read_b128 v[130:133], v137
	ds_read_b128 v[142:145], v137 offset:2048
	ds_read_b128 v[146:149], v0 offset:8192
	ds_read_b128 v[150:153], v0 offset:10240
	ds_read_b128 v[154:157], v0 offset:12288
	ds_read_b128 v[158:161], v0 offset:14336
	v_add_u32_e32 v0, s6, v138
	v_add_u32_e32 v137, v0, v140
	v_add_u32_e32 v0, v0, v139
	s_and_b32 s6, s31, 0xfffff80
	s_waitcnt lgkmcnt(0)
	v_mfma_f32_32x32x16_bf16 v[82:97], v[130:133], v[146:149], v[82:97]
	v_mfma_f32_32x32x16_bf16 v[114:129], v[142:145], v[146:149], v[114:129]
	v_mfma_f32_32x32x16_bf16 v[50:65], v[130:133], v[150:153], v[50:65]
	v_mfma_f32_32x32x16_bf16 v[18:33], v[130:133], v[154:157], v[18:33]
	v_mfma_f32_32x32x16_bf16 v[2:17], v[130:133], v[158:161], v[2:17]
	v_mfma_f32_32x32x16_bf16 v[98:113], v[142:145], v[150:153], v[98:113]
	v_mfma_f32_32x32x16_bf16 v[66:81], v[142:145], v[154:157], v[66:81]
	v_mfma_f32_32x32x16_bf16 v[34:49], v[142:145], v[158:161], v[34:49]
	ds_read_b128 v[130:133], v137
	ds_read_b128 v[140:143], v137 offset:2048
	ds_read_b128 v[144:147], v0 offset:8192
	ds_read_b128 v[148:151], v0 offset:10240
	ds_read_b128 v[152:155], v0 offset:12288
	ds_read_b128 v[156:159], v0 offset:14336
	v_or_b32_e32 v0, s6, v136
	s_lshl_b32 s6, s33, 7
	s_add_i32 s6, s6, 0
	v_mul_lo_u32 v0, v0, s0
	s_waitcnt vmcnt(0) lgkmcnt(0)
	v_mfma_f32_32x32x16_bf16 v[82:97], v[130:133], v[144:147], v[82:97]
	s_barrier
	v_mfma_f32_32x32x16_bf16 v[114:129], v[140:143], v[144:147], v[114:129]
	s_nop 9
	v_cvt_pk_bf16_f32 v82, v82, v83
	v_cvt_pk_bf16_f32 v83, v84, v85
	v_cvt_pk_bf16_f32 v84, v86, v87
	v_cvt_pk_bf16_f32 v85, v88, v89
	v_mfma_f32_32x32x16_bf16 v[50:65], v[130:133], v[148:151], v[50:65]
	v_mfma_f32_32x32x16_bf16 v[18:33], v[130:133], v[152:155], v[18:33]
	s_nop 10
	v_cvt_pk_bf16_f32 v50, v50, v51
	v_cvt_pk_bf16_f32 v51, v52, v53
	v_cvt_pk_bf16_f32 v52, v54, v55
	v_cvt_pk_bf16_f32 v53, v56, v57
	v_mfma_f32_32x32x16_bf16 v[2:17], v[130:133], v[156:159], v[2:17]
	v_lshlrev_b32_e32 v130, 3, v135
	v_add3_u32 v0, s6, v130, v0
	ds_write2_b64 v0, v[82:83], v[84:85] offset1:2
	v_cvt_pk_bf16_f32 v82, v90, v91
	v_cvt_pk_bf16_f32 v83, v92, v93
	v_cvt_pk_bf16_f32 v84, v94, v95
	v_cvt_pk_bf16_f32 v85, v96, v97
	v_mfma_f32_32x32x16_bf16 v[34:49], v[140:143], v[156:159], v[34:49]
	ds_write2_b64 v0, v[82:83], v[84:85] offset0:4 offset1:6
	v_cvt_pk_bf16_f32 v82, v114, v115
	v_cvt_pk_bf16_f32 v83, v116, v117
	v_cvt_pk_bf16_f32 v84, v118, v119
	v_cvt_pk_bf16_f32 v85, v120, v121
	ds_write2_b64 v0, v[82:83], v[84:85] offset0:8 offset1:10
	v_cvt_pk_bf16_f32 v82, v122, v123
	v_cvt_pk_bf16_f32 v83, v124, v125
	v_cvt_pk_bf16_f32 v84, v126, v127
	v_cvt_pk_bf16_f32 v85, v128, v129
	ds_write2_b64 v0, v[82:83], v[84:85] offset0:12 offset1:14
	v_add_u32_e32 v54, 0x2000, v0
	v_cvt_pk_bf16_f32 v18, v18, v19
	v_cvt_pk_bf16_f32 v19, v20, v21
	v_cvt_pk_bf16_f32 v20, v22, v23
	v_add_u32_e32 v22, 0x4000, v0
	v_cvt_pk_bf16_f32 v2, v2, v3
	v_cvt_pk_bf16_f32 v3, v4, v5
	v_cvt_pk_bf16_f32 v4, v6, v7
	v_cvt_pk_bf16_f32 v5, v8, v9
	v_add_u32_e32 v0, 0x6000, v0
	ds_write2_b64 v0, v[2:3], v[4:5] offset0:192 offset1:194
	v_cvt_pk_bf16_f32 v2, v10, v11
	v_cvt_pk_bf16_f32 v3, v12, v13
	v_cvt_pk_bf16_f32 v4, v14, v15
	v_cvt_pk_bf16_f32 v5, v16, v17
	ds_write2_b64 v0, v[2:3], v[4:5] offset0:196 offset1:198
	v_cvt_pk_bf16_f32 v2, v34, v35
	v_cvt_pk_bf16_f32 v3, v36, v37
	v_cvt_pk_bf16_f32 v4, v38, v39
	v_cvt_pk_bf16_f32 v5, v40, v41
	ds_write2_b64 v0, v[2:3], v[4:5] offset0:200 offset1:202
	v_cvt_pk_bf16_f32 v2, v42, v43
	v_cvt_pk_bf16_f32 v3, v44, v45
	v_cvt_pk_bf16_f32 v4, v46, v47
	v_cvt_pk_bf16_f32 v5, v48, v49
	ds_write2_b64 v0, v[2:3], v[4:5] offset0:204 offset1:206
	v_and_b32_e32 v2, 64, v202
	v_and_b32_e32 v3, 15, v134
	v_add_u32_e32 v2, 64, v2
	v_cmp_eq_u32_e32 vcc, 0, v3
	v_xor_b32_e32 v3, 1, v202
	v_cmp_lt_i32_e64 s[6:7], v3, v2
	v_mfma_f32_32x32x16_bf16 v[66:81], v[140:143], v[152:155], v[66:81]
	v_cvt_pk_bf16_f32 v21, v24, v25
	v_cndmask_b32_e64 v3, v202, v3, s[6:7]
	v_lshlrev_b32_e32 v15, 2, v3
	v_xor_b32_e32 v3, 2, v202
	v_cmp_lt_i32_e64 s[6:7], v3, v2
	v_lshlrev_b32_e32 v0, 3, v134
	v_and_b32_e32 v4, 0x78, v0
	v_cndmask_b32_e64 v3, v202, v3, s[6:7]
	v_lshlrev_b32_e32 v24, 2, v3
	v_xor_b32_e32 v3, 4, v202
	v_cmp_lt_i32_e64 s[6:7], v3, v2
	v_mfma_f32_32x32x16_bf16 v[98:113], v[140:143], v[148:151], v[98:113]
	v_or_b32_sdwa v0, s30, v4 dst_sel:WORD_1 dst_unused:UNUSED_PAD src0_sel:DWORD src1_sel:DWORD
	v_cndmask_b32_e64 v3, v202, v3, s[6:7]
	v_lshlrev_b32_e32 v25, 2, v3
	v_xor_b32_e32 v3, 8, v202
	v_cmp_lt_i32_e64 s[6:7], v3, v2
	v_and_b32_e32 v0, 0x3e00000, v0
	ds_write2_b64 v22, v[18:19], v[20:21] offset0:128 offset1:130
	v_cndmask_b32_e64 v2, v202, v3, s[6:7]
	v_cvt_pk_bf16_f32 v18, v26, v27
	v_cvt_pk_bf16_f32 v19, v28, v29
	v_cvt_pk_bf16_f32 v20, v30, v31
	v_cvt_pk_bf16_f32 v21, v32, v33
	v_lshlrev_b32_e32 v26, 2, v2
	v_lshl_add_u64 v[2:3], s[22:23], 0, v[0:1]
	v_lshlrev_b32_e32 v0, 4, v134
	s_lshl_b32 s6, s30, 2
	ds_write2_b64 v22, v[18:19], v[20:21] offset0:132 offset1:134
	v_cvt_pk_bf16_f32 v18, v66, v67
	v_cvt_pk_bf16_f32 v19, v68, v69
	v_cvt_pk_bf16_f32 v20, v70, v71
	v_cvt_pk_bf16_f32 v21, v72, v73
	v_and_b32_e32 v0, 48, v0
	s_add_u32 s6, s4, s6
	ds_write2_b64 v22, v[18:19], v[20:21] offset0:136 offset1:138
	v_cvt_pk_bf16_f32 v18, v74, v75
	v_cvt_pk_bf16_f32 v19, v76, v77
	v_cvt_pk_bf16_f32 v20, v78, v79
	v_cvt_pk_bf16_f32 v21, v80, v81
	v_lshl_add_u64 v[16:17], v[2:3], 0, v[0:1]
	s_addc_u32 s7, s5, 0
	v_lshlrev_b32_e32 v0, 2, v4
	ds_write2_b64 v54, v[50:51], v[52:53] offset0:64 offset1:66
	v_cvt_pk_bf16_f32 v50, v58, v59
	v_cvt_pk_bf16_f32 v51, v60, v61
	v_cvt_pk_bf16_f32 v52, v62, v63
	v_cvt_pk_bf16_f32 v53, v64, v65
	ds_write2_b64 v22, v[18:19], v[20:21] offset0:140 offset1:142
	v_lshl_add_u64 v[18:19], s[6:7], 0, v[0:1]
	s_and_b64 s[10:11], vcc, s[72:73]
	s_lshl_b32 s6, s29, 2
	ds_write2_b64 v54, v[50:51], v[52:53] offset0:68 offset1:70
	v_cvt_pk_bf16_f32 v50, v98, v99
	v_cvt_pk_bf16_f32 v51, v100, v101
	v_cvt_pk_bf16_f32 v52, v102, v103
	v_cvt_pk_bf16_f32 v53, v104, v105
	s_add_u32 s54, s18, s6
	ds_write2_b64 v54, v[50:51], v[52:53] offset0:72 offset1:74
	v_cvt_pk_bf16_f32 v50, v106, v107
	v_cvt_pk_bf16_f32 v51, v108, v109
	v_cvt_pk_bf16_f32 v52, v110, v111
	v_cvt_pk_bf16_f32 v53, v112, v113
	v_lshl_add_u32 v14, v4, 1, 0
	s_addc_u32 s55, s19, 0
	ds_write2_b64 v54, v[50:51], v[52:53] offset0:76 offset1:78
	s_waitcnt lgkmcnt(0)
	s_barrier
